# Wo / down-proj tiles: residual lines touched (16 dword loads per lane, same addresses as the epilogue loads) after the tile's first DMA pair so the epilogue residual loads hit L2; the 3 following coun
# speedup vs baseline: 1.0003x; 1.0003x over previous
; #define PG8_STAGE(bufoff, gbase, voff) do { _Pragma("unroll") for (int _i = 0; _i < 2; ++_i) \
;         __builtin_amdgcn_global_load_lds((const unsigned*)((const char*)(gbase) + (voff)[_i]), (PG8_LAS unsigned*)(lds + (bufoff) + ldsw + _i * 8192), 16, 0, 0); } while (0)
; #define PG8_LDA(dst, b, h) do { _Pragma("unroll") for (int m = 0; m < 4; ++m) _Pragma("unroll") for (int k = 0; k < 2; ++k) dst[m][k] = *(const PG8_LAS bf16x8*)(lds + PG8_SA(b, h) + aoff + m * 2048 + k * 1024); } while (0)
; #define PG8_LDB(dst, b, h) do { _Pragma("unroll") for (int n = 0; n < 2; ++n) _Pragma("unroll") for (int k = 0; k < 2; ++k) dst[n][k] = *(const PG8_LAS bf16x8*)(lds + PG8_SB(b, h) + boff + n * 2048 + k * 1024); } while (0)
; #define PG8_MMA(ai, bj, At, Bt) do { __builtin_amdgcn_s_setprio(1); _Pragma("unroll") for (int m = 0; m < 4; ++m) _Pragma("unroll") for (int n = 0; n < 2; ++n) _Pragma("unroll") for (int k = 0; k < 2; ++k) \
;         acc[ai][bj][m][n] = __builtin_amdgcn_mfma_f32_16x16x32_bf16(Bt[n][k], At[m][k], acc[ai][bj][m][n], 0, 0, 0); __builtin_amdgcn_s_setprio(0); } while (0)
; #define PG8_BAR __builtin_amdgcn_s_barrier()
;     __device__ __forceinline__ void operator()(const f32x4 (&acc)[2][2][4][2], const Unit& u, int wr, int wc, int fr_, int fq_) const {
;     ...
;         const size_t off0 = (size_t)(u.pm * BM + wr * 64 + fr) * 2048 + col0;
;         u32x4 bw[2][4][2];
; #pragma unroll
;         for (int ai = 0; ai < 2; ++ai)
; #pragma unroll
;             for (int m = 0; m < 4; ++m)
; #pragma unroll
;                 for (int bj = 0; bj < 2; ++bj) bw[ai][m][bj] = *(const u32x4*)(xb + off0 + (size_t)(ai * HALF + m * 16) * 2048 + bj * HALF);
; template <class Epi, class Sched, bool ALIGN_EPI = false, bool SP2 = false>
; __device__ __forceinline__ void gemm_phase(PG8_LAS unsigned char* lds, const Gemm g, const Sched& S, const Epi& E, int wave_s) {
;     ...
;             PG8_LDB(B0, 0, 0); PG8_LDB(B1, 0, 1); PG8_SCHED; PG8_LDA(At, 0, 0); PG8_STAGE(PG8_SA(1, 1), a1 + hstepA, voffA);
;             PG8_WAIT_V(8); PG8_WAIT_L(0); PG8_BAR; PG8_MMA(0, 0, At, B0); PG8_MMA(0, 1, At, B1); PG8_BAR; PG8_SCHED;
;             PG8_LDA(At, 0, 1); PG8_STAGE(PG8_SB(0, 0), b2, voffB); PG8_STAGE(PG8_SB(0, 1), b2 + hstepB, voffB); PG8_STAGE(PG8_SA(0, 0), a2, voffA);
;             PG8_WAIT_V(8); PG8_WAIT_L(0); PG8_BAR; PG8_MMA(1, 0, At, B0); PG8_MMA(1, 1, At, B1); PG8_BAR; PG8_SCHED;
.LBB0_601:
	s_ashr_i32 s21, s20, 31
	s_lshl_b64 s[2:3], s[20:21], 20
	s_add_u32 s88, s22, s2
	s_addc_u32 s89, s23, s3
	s_and_b64 s[2:3], s[4:5], exec
	s_cselect_b32 s2, s89, s31
	s_cselect_b32 s3, s88, s30
	s_add_u32 s4, s40, 0x80080
	s_addc_u32 s5, s41, 0
	s_add_u32 s21, s30, 0x100
	s_addc_u32 s27, s31, 0
	s_mov_b32 s81, -2
	s_add_u32 s30, s4, 0xfff80080
	s_addc_u32 s31, s5, -1
	s_add_i32 s84, 0, 0x10000
	s_cmp_eq_u32 s81, 28
	s_cselect_b32 s41, s29, s31
	s_cselect_b32 s40, s28, s30
	s_cselect_b32 s31, s2, s27
	s_cselect_b32 s30, s3, s21
	s_add_i32 s90, 0, 0x14000
	v_add_u32_e32 v134, s84, v207
	v_add_u32_e32 v158, s90, v207
	ds_read_b128 v[118:121], v134
	ds_read_b128 v[126:129], v134 offset:1024
	ds_read_b128 v[130:133], v134 offset:2048
	ds_read_b128 v[134:137], v134 offset:3072
	ds_read_b128 v[138:141], v158
	ds_read_b128 v[142:145], v158 offset:1024
	ds_read_b128 v[154:157], v158 offset:2048
	ds_read_b128 v[158:161], v158 offset:3072
	v_lshl_add_u64 v[210:211], s[4:5], 0, v[198:199]
	s_add_i32 m0, s35, 0xc000
	ds_read_b128 v[162:165], v208
	ds_read_b128 v[166:169], v208 offset:1024
	ds_read_b128 v[170:173], v208 offset:2048
	ds_read_b128 v[174:177], v208 offset:3072
	ds_read_b128 v[178:181], v208 offset:4096
	ds_read_b128 v[182:185], v208 offset:5120
	ds_read_b128 v[186:189], v208 offset:6144
	ds_read_b128 v[202:205], v208 offset:7168
	global_load_lds_dwordx4 v[210:211], off
	v_lshl_add_u64 v[210:211], s[4:5], 0, v[200:201]
	s_add_i32 m0, s35, 0xe000
	s_nop 0
	global_load_lds_dwordx4 v[210:211], off
	s_lshl_b32 s32, s50, 8
	s_or_b32 s32, s32, s45
	v_lshl_add_u32 v220, v1, 3, s32
	s_lshl_b32 s32, s80, 8
	s_add_i32 s32, s32, s44
	v_add_u32_e32 v221, s32, v206
	v_lshl_add_u32 v220, v221, 11, v220
	v_lshlrev_b32_e32 v220, 1, v220
	global_load_dword v254, v220, s[10:11]
	global_load_dword v254, v220, s[10:11] offset:256
	v_add_u32_e32 v221, s24, v220
	global_load_dword v254, v221, s[10:11]
	global_load_dword v254, v221, s[10:11] offset:256
	v_add_u32_e32 v221, s19, v220
	global_load_dword v254, v221, s[10:11]
	global_load_dword v254, v221, s[10:11] offset:256
	v_add_u32_e32 v221, s25, v220
	global_load_dword v254, v221, s[10:11]
	global_load_dword v254, v221, s[10:11] offset:256
	v_add_u32_e32 v221, s1, v220
	global_load_dword v254, v221, s[10:11]
	global_load_dword v254, v221, s[10:11] offset:256
	v_add_u32_e32 v221, s0, v220
	global_load_dword v254, v221, s[10:11]
	global_load_dword v254, v221, s[10:11] offset:256
	v_add_u32_e32 v221, s64, v220
	global_load_dword v254, v221, s[10:11]
	global_load_dword v254, v221, s[10:11] offset:256
	v_add_u32_e32 v221, s65, v220
	global_load_dword v254, v221, s[10:11]
	global_load_dword v254, v221, s[10:11] offset:256
	s_waitcnt vmcnt(24)
	s_waitcnt lgkmcnt(0)
	s_barrier
	s_waitcnt lgkmcnt(0)
	v_mfma_f32_16x16x32_bf16 v[150:153], v[118:121], v[162:165], 0
	v_mfma_f32_16x16x32_bf16 v[146:149], v[130:133], v[162:165], 0
	v_mfma_f32_16x16x32_bf16 v[110:113], v[118:121], v[170:173], 0
	v_mfma_f32_16x16x32_bf16 v[106:109], v[130:133], v[170:173], 0
	v_mfma_f32_16x16x32_bf16 v[94:97], v[118:121], v[178:181], 0
	v_mfma_f32_16x16x32_bf16 v[90:93], v[130:133], v[178:181], 0
	v_mfma_f32_16x16x32_bf16 v[78:81], v[118:121], v[186:189], 0
	v_mfma_f32_16x16x32_bf16 v[74:77], v[130:133], v[186:189], 0
	v_mfma_f32_16x16x32_bf16 v[150:153], v[126:129], v[166:169], v[150:153]
	v_mfma_f32_16x16x32_bf16 v[146:149], v[134:137], v[166:169], v[146:149]
	v_mfma_f32_16x16x32_bf16 v[110:113], v[126:129], v[174:177], v[110:113]
	v_mfma_f32_16x16x32_bf16 v[106:109], v[134:137], v[174:177], v[106:109]
	v_mfma_f32_16x16x32_bf16 v[94:97], v[126:129], v[182:185], v[94:97]
	v_mfma_f32_16x16x32_bf16 v[90:93], v[134:137], v[182:185], v[90:93]
	v_mfma_f32_16x16x32_bf16 v[78:81], v[126:129], v[202:205], v[78:81]
	v_mfma_f32_16x16x32_bf16 v[74:77], v[134:137], v[202:205], v[74:77]
	v_mfma_f32_16x16x32_bf16 v[122:125], v[138:141], v[162:165], 0
	v_mfma_f32_16x16x32_bf16 v[114:117], v[154:157], v[162:165], 0
	v_mfma_f32_16x16x32_bf16 v[102:105], v[138:141], v[170:173], 0
	v_mfma_f32_16x16x32_bf16 v[98:101], v[154:157], v[170:173], 0
	v_mfma_f32_16x16x32_bf16 v[86:89], v[138:141], v[178:181], 0
	v_mfma_f32_16x16x32_bf16 v[82:85], v[154:157], v[178:181], 0
	v_mfma_f32_16x16x32_bf16 v[70:73], v[138:141], v[186:189], 0
	v_mfma_f32_16x16x32_bf16 v[66:69], v[154:157], v[186:189], 0
	v_mfma_f32_16x16x32_bf16 v[122:125], v[142:145], v[166:169], v[122:125]
	v_mfma_f32_16x16x32_bf16 v[114:117], v[158:161], v[166:169], v[114:117]
	v_mfma_f32_16x16x32_bf16 v[102:105], v[142:145], v[174:177], v[102:105]
	v_mfma_f32_16x16x32_bf16 v[98:101], v[158:161], v[174:177], v[98:101]
	v_mfma_f32_16x16x32_bf16 v[86:89], v[142:145], v[182:185], v[86:89]
	v_mfma_f32_16x16x32_bf16 v[82:85], v[158:161], v[182:185], v[82:85]
	v_mfma_f32_16x16x32_bf16 v[70:73], v[142:145], v[202:205], v[70:73]
	v_mfma_f32_16x16x32_bf16 v[66:69], v[158:161], v[202:205], v[66:69]
	s_barrier
	s_add_i32 s84, s84, s34
	v_lshl_add_u64 v[210:211], s[30:31], 0, v[194:195]
	s_mov_b32 m0, s84
	ds_read_b128 v[162:165], v208 offset:16384
	ds_read_b128 v[166:169], v208 offset:17408
	ds_read_b128 v[170:173], v208 offset:18432
	ds_read_b128 v[174:177], v208 offset:19456
	ds_read_b128 v[178:181], v208 offset:20480
	ds_read_b128 v[182:185], v208 offset:21504
	ds_read_b128 v[186:189], v208 offset:22528
	ds_read_b128 v[202:205], v208 offset:23552
	global_load_lds_dwordx4 v[210:211], off
	s_add_i32 m0, s84, 0x2000
	s_add_u32 s84, s30, 0x80000
	v_lshl_add_u64 v[212:213], s[30:31], 0, v[190:191]
	s_addc_u32 s85, s31, 0
	s_add_i32 s90, s90, s34
	global_load_lds_dwordx4 v[212:213], off
	v_lshl_add_u64 v[214:215], s[84:85], 0, v[194:195]
	s_mov_b32 m0, s90
	v_lshl_add_u64 v[216:217], s[40:41], 0, v[192:193]
	global_load_lds_dwordx4 v[214:215], off
	v_lshl_add_u64 v[214:215], s[84:85], 0, v[190:191]
	s_add_i32 m0, s90, 0x2000
	s_nop 0
	global_load_lds_dwordx4 v[214:215], off
	v_lshl_add_u64 v[214:215], s[40:41], 0, v[196:197]
	s_mov_b32 m0, s35
	s_nop 0
	global_load_lds_dwordx4 v[214:215], off
	s_mov_b32 m0, s36
	s_nop 0
	global_load_lds_dwordx4 v[216:217], off
	s_waitcnt vmcnt(24)
	s_waitcnt lgkmcnt(0)
	s_barrier
; #define PG8_STAGE(bufoff, gbase, voff) do { _Pragma("unroll") for (int _i = 0; _i < 2; ++_i) \
;         __builtin_amdgcn_global_load_lds((const unsigned*)((const char*)(gbase) + (voff)[_i]), (PG8_LAS unsigned*)(lds + (bufoff) + ldsw + _i * 8192), 16, 0, 0); } while (0)
; #define PG8_LDA(dst, b, h) do { _Pragma("unroll") for (int m = 0; m < 4; ++m) _Pragma("unroll") for (int k = 0; k < 2; ++k) dst[m][k] = *(const PG8_LAS bf16x8*)(lds + PG8_SA(b, h) + aoff + m * 2048 + k * 1024); } while (0)
; #define PG8_LDB(dst, b, h) do { _Pragma("unroll") for (int n = 0; n < 2; ++n) _Pragma("unroll") for (int k = 0; k < 2; ++k) dst[n][k] = *(const PG8_LAS bf16x8*)(lds + PG8_SB(b, h) + boff + n * 2048 + k * 1024); } while (0)
; #define PG8_MMA(ai, bj, At, Bt) do { __builtin_amdgcn_s_setprio(1); _Pragma("unroll") for (int m = 0; m < 4; ++m) _Pragma("unroll") for (int n = 0; n < 2; ++n) _Pragma("unroll") for (int k = 0; k < 2; ++k) \
;         acc[ai][bj][m][n] = __builtin_amdgcn_mfma_f32_16x16x32_bf16(Bt[n][k], At[m][k], acc[ai][bj][m][n], 0, 0, 0); __builtin_amdgcn_s_setprio(0); } while (0)
; #define PG8_WAIT_V(n) asm volatile("s_waitcnt vmcnt(" #n ")" ::: "memory")
; #define PG8_WAIT_L(n) asm volatile("s_waitcnt lgkmcnt(" #n ")" ::: "memory")
; #define PG8_BAR __builtin_amdgcn_s_barrier()
; #define PG8_SCHED __builtin_amdgcn_sched_barrier(0)
; template <class Epi, class Sched, bool ALIGN_EPI = false, bool SP2 = false>
; __device__ __forceinline__ void gemm_phase(PG8_LAS unsigned char* lds, const Gemm g, const Sched& S, const Epi& E, int wave_s) {
;     ...
;             PG8_WAIT_V(8); PG8_WAIT_L(0); PG8_BAR; PG8_MMA(1, 0, At, B0); PG8_MMA(1, 1, At, B1); PG8_BAR; PG8_SCHED;
;             PG8_LDB(B0, 1, 0); PG8_LDB(B1, 1, 1); PG8_SCHED; PG8_LDA(At, 1, 0); PG8_STAGE(PG8_SA(0, 1), a2 + hstepA, voffA);
;             PG8_WAIT_V(8); PG8_WAIT_L(0); PG8_BAR; PG8_MMA(0, 0, At, B0); PG8_MMA(0, 1, At, B1); PG8_BAR; PG8_SCHED;
;             PG8_LDA(At, 1, 1); PG8_STAGE(PG8_SB(1, 0), b3, voffB); PG8_STAGE(PG8_SB(1, 1), b3 + hstepB, voffB); PG8_STAGE(PG8_SA(1, 0), a3, voffA);
	s_waitcnt lgkmcnt(0)
	v_mfma_f32_16x16x32_bf16 v[62:65], v[118:121], v[162:165], 0
	v_mfma_f32_16x16x32_bf16 v[58:61], v[130:133], v[162:165], 0
	v_mfma_f32_16x16x32_bf16 v[46:49], v[118:121], v[170:173], 0
	v_mfma_f32_16x16x32_bf16 v[42:45], v[130:133], v[170:173], 0
	v_mfma_f32_16x16x32_bf16 v[30:33], v[118:121], v[178:181], 0
	v_mfma_f32_16x16x32_bf16 v[26:29], v[130:133], v[178:181], 0
	v_mfma_f32_16x16x32_bf16 v[14:17], v[118:121], v[186:189], 0
	v_mfma_f32_16x16x32_bf16 v[10:13], v[130:133], v[186:189], 0
	v_mfma_f32_16x16x32_bf16 v[62:65], v[126:129], v[166:169], v[62:65]
	v_mfma_f32_16x16x32_bf16 v[58:61], v[134:137], v[166:169], v[58:61]
	v_mfma_f32_16x16x32_bf16 v[46:49], v[126:129], v[174:177], v[46:49]
	v_mfma_f32_16x16x32_bf16 v[42:45], v[134:137], v[174:177], v[42:45]
	v_mfma_f32_16x16x32_bf16 v[30:33], v[126:129], v[182:185], v[30:33]
	v_mfma_f32_16x16x32_bf16 v[26:29], v[134:137], v[182:185], v[26:29]
	v_mfma_f32_16x16x32_bf16 v[14:17], v[126:129], v[202:205], v[14:17]
	v_mfma_f32_16x16x32_bf16 v[10:13], v[134:137], v[202:205], v[10:13]
	v_mfma_f32_16x16x32_bf16 v[54:57], v[138:141], v[162:165], 0
	v_mfma_f32_16x16x32_bf16 v[50:53], v[154:157], v[162:165], 0
	v_mfma_f32_16x16x32_bf16 v[38:41], v[138:141], v[170:173], 0
	v_mfma_f32_16x16x32_bf16 v[34:37], v[154:157], v[170:173], 0
	v_mfma_f32_16x16x32_bf16 v[22:25], v[138:141], v[178:181], 0
	v_mfma_f32_16x16x32_bf16 v[18:21], v[154:157], v[178:181], 0
	v_mfma_f32_16x16x32_bf16 v[6:9], v[138:141], v[186:189], 0
	v_mfma_f32_16x16x32_bf16 v[2:5], v[154:157], v[186:189], 0
	v_mfma_f32_16x16x32_bf16 v[54:57], v[142:145], v[166:169], v[54:57]
	v_mfma_f32_16x16x32_bf16 v[50:53], v[158:161], v[166:169], v[50:53]
	v_mfma_f32_16x16x32_bf16 v[38:41], v[142:145], v[174:177], v[38:41]
	v_mfma_f32_16x16x32_bf16 v[34:37], v[158:161], v[174:177], v[34:37]
	v_mfma_f32_16x16x32_bf16 v[22:25], v[142:145], v[182:185], v[22:25]
	v_mfma_f32_16x16x32_bf16 v[18:21], v[158:161], v[182:185], v[18:21]
	v_mfma_f32_16x16x32_bf16 v[6:9], v[142:145], v[202:205], v[6:9]
	v_mfma_f32_16x16x32_bf16 v[2:5], v[158:161], v[202:205], v[2:5]
	s_barrier
	s_add_i32 s84, 0, 0x18000
	s_add_i32 s85, 0, 0x1c000
	v_add_u32_e32 v134, s84, v207
	v_add_u32_e32 v158, s85, v207
	ds_read_b128 v[118:121], v134
	ds_read_b128 v[126:129], v134 offset:1024
	ds_read_b128 v[130:133], v134 offset:2048
	ds_read_b128 v[134:137], v134 offset:3072
	ds_read_b128 v[138:141], v158
	ds_read_b128 v[142:145], v158 offset:1024
	ds_read_b128 v[154:157], v158 offset:2048
	ds_read_b128 v[158:161], v158 offset:3072
	s_add_u32 s40, s40, 0x80000
	s_addc_u32 s41, s41, 0
	s_mov_b32 m0, s37
	v_lshl_add_u64 v[218:219], s[40:41], 0, v[196:197]
	ds_read_b128 v[162:165], v208 offset:32768
	ds_read_b128 v[166:169], v208 offset:33792
	ds_read_b128 v[170:173], v208 offset:34816
	ds_read_b128 v[174:177], v208 offset:35840
	ds_read_b128 v[178:181], v208 offset:36864
	ds_read_b128 v[182:185], v208 offset:37888
	ds_read_b128 v[186:189], v208 offset:38912
	ds_read_b128 v[202:205], v208 offset:39936
	global_load_lds_dwordx4 v[218:219], off
	v_lshl_add_u64 v[218:219], s[40:41], 0, v[192:193]
	s_mov_b32 m0, s42
	s_nop 0
	global_load_lds_dwordx4 v[218:219], off
	s_waitcnt vmcnt(24)
	s_waitcnt lgkmcnt(0)
	s_barrier
	s_waitcnt lgkmcnt(0)
	v_mfma_f32_16x16x32_bf16 v[150:153], v[118:121], v[162:165], v[150:153]
	v_mfma_f32_16x16x32_bf16 v[146:149], v[130:133], v[162:165], v[146:149]
	v_mfma_f32_16x16x32_bf16 v[110:113], v[118:121], v[170:173], v[110:113]
	v_mfma_f32_16x16x32_bf16 v[106:109], v[130:133], v[170:173], v[106:109]
	v_mfma_f32_16x16x32_bf16 v[94:97], v[118:121], v[178:181], v[94:97]
	v_mfma_f32_16x16x32_bf16 v[90:93], v[130:133], v[178:181], v[90:93]
	v_mfma_f32_16x16x32_bf16 v[78:81], v[118:121], v[186:189], v[78:81]
	v_mfma_f32_16x16x32_bf16 v[74:77], v[130:133], v[186:189], v[74:77]
	v_mfma_f32_16x16x32_bf16 v[150:153], v[126:129], v[166:169], v[150:153]
	v_mfma_f32_16x16x32_bf16 v[146:149], v[134:137], v[166:169], v[146:149]
	v_mfma_f32_16x16x32_bf16 v[110:113], v[126:129], v[174:177], v[110:113]
	v_mfma_f32_16x16x32_bf16 v[106:109], v[134:137], v[174:177], v[106:109]
	v_mfma_f32_16x16x32_bf16 v[94:97], v[126:129], v[182:185], v[94:97]
	v_mfma_f32_16x16x32_bf16 v[90:93], v[134:137], v[182:185], v[90:93]
	v_mfma_f32_16x16x32_bf16 v[78:81], v[126:129], v[202:205], v[78:81]
	v_mfma_f32_16x16x32_bf16 v[74:77], v[134:137], v[202:205], v[74:77]
	v_mfma_f32_16x16x32_bf16 v[122:125], v[138:141], v[162:165], v[122:125]
	v_mfma_f32_16x16x32_bf16 v[114:117], v[154:157], v[162:165], v[114:117]
	v_mfma_f32_16x16x32_bf16 v[102:105], v[138:141], v[170:173], v[102:105]
	v_mfma_f32_16x16x32_bf16 v[98:101], v[154:157], v[170:173], v[98:101]
	v_mfma_f32_16x16x32_bf16 v[86:89], v[138:141], v[178:181], v[86:89]
	v_mfma_f32_16x16x32_bf16 v[82:85], v[154:157], v[178:181], v[82:85]
	v_mfma_f32_16x16x32_bf16 v[70:73], v[138:141], v[186:189], v[70:73]
	v_mfma_f32_16x16x32_bf16 v[66:69], v[154:157], v[186:189], v[66:69]
	v_mfma_f32_16x16x32_bf16 v[122:125], v[142:145], v[166:169], v[122:125]
	v_mfma_f32_16x16x32_bf16 v[114:117], v[158:161], v[166:169], v[114:117]
	v_mfma_f32_16x16x32_bf16 v[102:105], v[142:145], v[174:177], v[102:105]
	v_mfma_f32_16x16x32_bf16 v[98:101], v[158:161], v[174:177], v[98:101]
	v_mfma_f32_16x16x32_bf16 v[86:89], v[142:145], v[182:185], v[86:89]
	v_mfma_f32_16x16x32_bf16 v[82:85], v[158:161], v[182:185], v[82:85]
	v_mfma_f32_16x16x32_bf16 v[70:73], v[142:145], v[202:205], v[70:73]
	v_mfma_f32_16x16x32_bf16 v[66:69], v[158:161], v[202:205], v[66:69]
	s_barrier
; #define PG8_STAGE(bufoff, gbase, voff) do { _Pragma("unroll") for (int _i = 0; _i < 2; ++_i) \
;         __builtin_amdgcn_global_load_lds((const unsigned*)((const char*)(gbase) + (voff)[_i]), (PG8_LAS unsigned*)(lds + (bufoff) + ldsw + _i * 8192), 16, 0, 0); } while (0)
; #define PG8_LDA(dst, b, h) do { _Pragma("unroll") for (int m = 0; m < 4; ++m) _Pragma("unroll") for (int k = 0; k < 2; ++k) dst[m][k] = *(const PG8_LAS bf16x8*)(lds + PG8_SA(b, h) + aoff + m * 2048 + k * 1024); } while (0)
; #define PG8_MMA(ai, bj, At, Bt) do { __builtin_amdgcn_s_setprio(1); _Pragma("unroll") for (int m = 0; m < 4; ++m) _Pragma("unroll") for (int n = 0; n < 2; ++n) _Pragma("unroll") for (int k = 0; k < 2; ++k) \
;         acc[ai][bj][m][n] = __builtin_amdgcn_mfma_f32_16x16x32_bf16(Bt[n][k], At[m][k], acc[ai][bj][m][n], 0, 0, 0); __builtin_amdgcn_s_setprio(0); } while (0)
; #define PG8_WAIT_V(n) asm volatile("s_waitcnt vmcnt(" #n ")" ::: "memory")
; #define PG8_WAIT_L(n) asm volatile("s_waitcnt lgkmcnt(" #n ")" ::: "memory")
; #define PG8_BAR __builtin_amdgcn_s_barrier()
; #define PG8_SCHED __builtin_amdgcn_sched_barrier(0)
; template <class Epi, class Sched, bool ALIGN_EPI = false, bool SP2 = false>
; __device__ __forceinline__ void gemm_phase(PG8_LAS unsigned char* lds, const Gemm g, const Sched& S, const Epi& E, int wave_s) {
;     ...
;             PG8_LDA(At, 1, 1); PG8_STAGE(PG8_SB(1, 0), b3, voffB); PG8_STAGE(PG8_SB(1, 1), b3 + hstepB, voffB); PG8_STAGE(PG8_SA(1, 0), a3, voffA);
;             PG8_WAIT_V(8); PG8_WAIT_L(0); PG8_BAR; PG8_MMA(1, 0, At, B0); PG8_MMA(1, 1, At, B1); PG8_BAR; PG8_SCHED;
	s_add_i32 s40, s84, s34
	v_lshl_add_u64 v[210:211], v[210:211], 0, s[60:61]
	s_mov_b32 m0, s40
	ds_read_b128 v[162:165], v208 offset:49152
	ds_read_b128 v[166:169], v208 offset:50176
	ds_read_b128 v[170:173], v208 offset:51200
	ds_read_b128 v[174:177], v208 offset:52224
	ds_read_b128 v[178:181], v208 offset:53248
	ds_read_b128 v[182:185], v208 offset:54272
	ds_read_b128 v[186:189], v208 offset:55296
	ds_read_b128 v[202:205], v208 offset:56320
	global_load_lds_dwordx4 v[210:211], off
	s_add_i32 m0, s40, 0x2000
	s_add_u32 s30, s30, 0x80080
	v_lshl_add_u64 v[210:211], v[212:213], 0, s[60:61]
	s_addc_u32 s31, s31, 0
	s_add_i32 s40, s85, s34
	global_load_lds_dwordx4 v[210:211], off
	v_lshl_add_u64 v[210:211], s[30:31], 0, v[194:195]
	s_mov_b32 m0, s40
	s_nop 0
	global_load_lds_dwordx4 v[210:211], off
	v_lshl_add_u64 v[210:211], s[30:31], 0, v[190:191]
	s_add_i32 m0, s40, 0x2000
	s_nop 0
	global_load_lds_dwordx4 v[210:211], off
	v_lshl_add_u64 v[210:211], v[214:215], 0, s[60:61]
	s_mov_b32 m0, s46
	s_nop 0
	global_load_lds_dwordx4 v[210:211], off
	v_lshl_add_u64 v[210:211], v[216:217], 0, s[60:61]
	s_mov_b32 m0, s47
	s_nop 0
	global_load_lds_dwordx4 v[210:211], off
	s_waitcnt vmcnt(8)
	s_waitcnt lgkmcnt(0)
	s_barrier
	s_waitcnt lgkmcnt(0)
	v_mfma_f32_16x16x32_bf16 v[62:65], v[118:121], v[162:165], v[62:65]
	v_mfma_f32_16x16x32_bf16 v[58:61], v[130:133], v[162:165], v[58:61]
	v_mfma_f32_16x16x32_bf16 v[46:49], v[118:121], v[170:173], v[46:49]
	v_mfma_f32_16x16x32_bf16 v[42:45], v[130:133], v[170:173], v[42:45]
	v_mfma_f32_16x16x32_bf16 v[30:33], v[118:121], v[178:181], v[30:33]
	v_mfma_f32_16x16x32_bf16 v[26:29], v[130:133], v[178:181], v[26:29]
	v_mfma_f32_16x16x32_bf16 v[14:17], v[118:121], v[186:189], v[14:17]
	v_mfma_f32_16x16x32_bf16 v[10:13], v[130:133], v[186:189], v[10:13]
	v_mfma_f32_16x16x32_bf16 v[62:65], v[126:129], v[166:169], v[62:65]
	v_mfma_f32_16x16x32_bf16 v[58:61], v[134:137], v[166:169], v[58:61]
	v_mfma_f32_16x16x32_bf16 v[46:49], v[126:129], v[174:177], v[46:49]
	v_mfma_f32_16x16x32_bf16 v[42:45], v[134:137], v[174:177], v[42:45]
	v_mfma_f32_16x16x32_bf16 v[30:33], v[126:129], v[182:185], v[30:33]
	v_mfma_f32_16x16x32_bf16 v[26:29], v[134:137], v[182:185], v[26:29]
	v_mfma_f32_16x16x32_bf16 v[14:17], v[126:129], v[202:205], v[14:17]
	v_mfma_f32_16x16x32_bf16 v[10:13], v[134:137], v[202:205], v[10:13]
	v_mfma_f32_16x16x32_bf16 v[54:57], v[138:141], v[162:165], v[54:57]
	v_mfma_f32_16x16x32_bf16 v[50:53], v[154:157], v[162:165], v[50:53]
	v_mfma_f32_16x16x32_bf16 v[38:41], v[138:141], v[170:173], v[38:41]
	v_mfma_f32_16x16x32_bf16 v[34:37], v[154:157], v[170:173], v[34:37]
	v_mfma_f32_16x16x32_bf16 v[22:25], v[138:141], v[178:181], v[22:25]
	v_mfma_f32_16x16x32_bf16 v[18:21], v[154:157], v[178:181], v[18:21]
	v_mfma_f32_16x16x32_bf16 v[6:9], v[138:141], v[186:189], v[6:9]
	v_mfma_f32_16x16x32_bf16 v[2:5], v[154:157], v[186:189], v[2:5]
	v_mfma_f32_16x16x32_bf16 v[54:57], v[142:145], v[166:169], v[54:57]
	v_mfma_f32_16x16x32_bf16 v[50:53], v[158:161], v[166:169], v[50:53]
	v_mfma_f32_16x16x32_bf16 v[38:41], v[142:145], v[174:177], v[38:41]
	v_mfma_f32_16x16x32_bf16 v[34:37], v[158:161], v[174:177], v[34:37]
	v_mfma_f32_16x16x32_bf16 v[22:25], v[142:145], v[182:185], v[22:25]
	v_mfma_f32_16x16x32_bf16 v[18:21], v[158:161], v[182:185], v[18:21]
	v_mfma_f32_16x16x32_bf16 v[6:9], v[142:145], v[202:205], v[6:9]
	v_mfma_f32_16x16x32_bf16 v[2:5], v[158:161], v[202:205], v[2:5]
	s_barrier
	s_add_i32 s81, s81, 2
	s_add_u32 s4, s4, 0x100
	s_addc_u32 s5, s5, 0
	s_add_u32 s21, s21, 0x100
	s_addc_u32 s27, s27, 0
	s_cmp_gt_u32 s81, 29

; #define PG8_STAGE(bufoff, gbase, voff) do { _Pragma("unroll") for (int _i = 0; _i < 2; ++_i) \
;         __builtin_amdgcn_global_load_lds((const unsigned*)((const char*)(gbase) + (voff)[_i]), (PG8_LAS unsigned*)(lds + (bufoff) + ldsw + _i * 8192), 16, 0, 0); } while (0)
; #define PG8_LDA(dst, b, h) do { _Pragma("unroll") for (int m = 0; m < 4; ++m) _Pragma("unroll") for (int k = 0; k < 2; ++k) dst[m][k] = *(const PG8_LAS bf16x8*)(lds + PG8_SA(b, h) + aoff + m * 2048 + k * 1024); } while (0)
; #define PG8_LDB(dst, b, h) do { _Pragma("unroll") for (int n = 0; n < 2; ++n) _Pragma("unroll") for (int k = 0; k < 2; ++k) dst[n][k] = *(const PG8_LAS bf16x8*)(lds + PG8_SB(b, h) + boff + n * 2048 + k * 1024); } while (0)
; #define PG8_MMA(ai, bj, At, Bt) do { __builtin_amdgcn_s_setprio(1); _Pragma("unroll") for (int m = 0; m < 4; ++m) _Pragma("unroll") for (int n = 0; n < 2; ++n) _Pragma("unroll") for (int k = 0; k < 2; ++k) \
;         acc[ai][bj][m][n] = __builtin_amdgcn_mfma_f32_16x16x32_bf16(Bt[n][k], At[m][k], acc[ai][bj][m][n], 0, 0, 0); __builtin_amdgcn_s_setprio(0); } while (0)
; #define PG8_BAR __builtin_amdgcn_s_barrier()
;     __device__ __forceinline__ void operator()(const f32x4 (&acc)[2][2][4][2], const Unit& u, int wr, int wc, int fr_, int fq_) const {
;     ...
;         const size_t off0 = (size_t)(u.pm * BM + wr * 64 + fr) * 2048 + col0;
;         u32x4 bw[2][4][2];
; #pragma unroll
;         for (int ai = 0; ai < 2; ++ai)
; #pragma unroll
;             for (int m = 0; m < 4; ++m)
; #pragma unroll
;                 for (int bj = 0; bj < 2; ++bj) bw[ai][m][bj] = *(const u32x4*)(xb + off0 + (size_t)(ai * HALF + m * 16) * 2048 + bj * HALF);
; template <class Epi, class Sched, bool ALIGN_EPI = false, bool SP2 = false>
; __device__ __forceinline__ void gemm_phase(PG8_LAS unsigned char* lds, const Gemm g, const Sched& S, const Epi& E, int wave_s) {
;     ...
;             PG8_LDB(B0, 0, 0); PG8_LDB(B1, 0, 1); PG8_SCHED; PG8_LDA(At, 0, 0); PG8_STAGE(PG8_SA(1, 1), a1 + hstepA, voffA);
;             PG8_WAIT_V(8); PG8_WAIT_L(0); PG8_BAR; PG8_MMA(0, 0, At, B0); PG8_MMA(0, 1, At, B1); PG8_BAR; PG8_SCHED;
;             PG8_LDA(At, 0, 1); PG8_STAGE(PG8_SB(0, 0), b2, voffB); PG8_STAGE(PG8_SB(0, 1), b2 + hstepB, voffB); PG8_STAGE(PG8_SA(0, 0), a2, voffA);
;             PG8_WAIT_V(8); PG8_WAIT_L(0); PG8_BAR; PG8_MMA(1, 0, At, B0); PG8_MMA(1, 1, At, B1); PG8_BAR; PG8_SCHED;
.LBB0_785:
	s_add_u32 s2, s30, 0x100
	s_addc_u32 s3, s31, 0
	s_mov_b32 s81, -2
	s_add_u32 s4, s8, 0x100
	s_addc_u32 s5, s9, 0
	s_add_i32 s84, 0, 0x10000
	s_cmpk_eq_i32 s81, 0x54
	s_cselect_b32 s31, s95, s5
	s_cselect_b32 s30, s94, s4
	s_cselect_b32 s7, s97, s3
	s_cselect_b32 s6, s96, s2
	s_add_i32 s85, 0, 0x14000
	v_add_u32_e32 v110, s84, v211
	v_add_u32_e32 v150, s85, v211
	ds_read_b128 v[78:81], v110
	ds_read_b128 v[86:89], v110 offset:1024
	ds_read_b128 v[102:105], v110 offset:2048
	ds_read_b128 v[110:113], v110 offset:3072
	ds_read_b128 v[122:125], v150
	ds_read_b128 v[134:137], v150 offset:1024
	ds_read_b128 v[146:149], v150 offset:2048
	ds_read_b128 v[150:153], v150 offset:3072
	v_lshl_add_u64 v[206:207], s[8:9], 0, v[198:199]
	s_add_i32 m0, s35, 0xc000
	ds_read_b128 v[162:165], v212
	ds_read_b128 v[166:169], v212 offset:1024
	ds_read_b128 v[170:173], v212 offset:2048
	ds_read_b128 v[174:177], v212 offset:3072
	ds_read_b128 v[178:181], v212 offset:4096
	ds_read_b128 v[182:185], v212 offset:5120
	ds_read_b128 v[186:189], v212 offset:6144
	ds_read_b128 v[202:205], v212 offset:7168
	global_load_lds_dwordx4 v[206:207], off
	v_lshl_add_u64 v[206:207], s[8:9], 0, v[200:201]
	s_add_i32 m0, s35, 0xe000
	s_nop 0
	global_load_lds_dwordx4 v[206:207], off
	s_lshl_b32 s32, s50, 8
	s_or_b32 s32, s32, s43
	v_lshl_add_u32 v220, v1, 3, s32
	s_lshl_b32 s32, s80, 8
	s_add_i32 s32, s32, s42
	v_add_u32_e32 v221, s32, v210
	v_lshl_add_u32 v220, v221, 11, v220
	v_lshlrev_b32_e32 v220, 1, v220
	global_load_dword v254, v220, s[28:29]
	global_load_dword v254, v220, s[28:29] offset:256
	v_add_u32_e32 v221, s24, v220
	global_load_dword v254, v221, s[28:29]
	global_load_dword v254, v221, s[28:29] offset:256
	v_add_u32_e32 v221, s19, v220
	global_load_dword v254, v221, s[28:29]
	global_load_dword v254, v221, s[28:29] offset:256
	v_add_u32_e32 v221, s25, v220
	global_load_dword v254, v221, s[28:29]
	global_load_dword v254, v221, s[28:29] offset:256
	v_add_u32_e32 v221, s1, v220
	global_load_dword v254, v221, s[28:29]
	global_load_dword v254, v221, s[28:29] offset:256
	v_add_u32_e32 v221, s0, v220
	global_load_dword v254, v221, s[28:29]
	global_load_dword v254, v221, s[28:29] offset:256
	v_add_u32_e32 v221, s64, v220
	global_load_dword v254, v221, s[28:29]
	global_load_dword v254, v221, s[28:29] offset:256
	v_add_u32_e32 v221, s65, v220
	global_load_dword v254, v221, s[28:29]
	global_load_dword v254, v221, s[28:29] offset:256
	s_waitcnt vmcnt(24)
	s_waitcnt lgkmcnt(0)
	s_barrier
	s_waitcnt lgkmcnt(0)
	v_mfma_f32_16x16x32_bf16 v[158:161], v[78:81], v[162:165], 0
	v_mfma_f32_16x16x32_bf16 v[154:157], v[102:105], v[162:165], 0
	v_mfma_f32_16x16x32_bf16 v[130:133], v[78:81], v[170:173], 0
	v_mfma_f32_16x16x32_bf16 v[126:129], v[102:105], v[170:173], 0
	v_mfma_f32_16x16x32_bf16 v[106:109], v[78:81], v[178:181], 0
	v_mfma_f32_16x16x32_bf16 v[98:101], v[102:105], v[178:181], 0
	v_mfma_f32_16x16x32_bf16 v[82:85], v[78:81], v[186:189], 0
	v_mfma_f32_16x16x32_bf16 v[74:77], v[102:105], v[186:189], 0
	v_mfma_f32_16x16x32_bf16 v[158:161], v[86:89], v[166:169], v[158:161]
	v_mfma_f32_16x16x32_bf16 v[154:157], v[110:113], v[166:169], v[154:157]
	v_mfma_f32_16x16x32_bf16 v[130:133], v[86:89], v[174:177], v[130:133]
	v_mfma_f32_16x16x32_bf16 v[126:129], v[110:113], v[174:177], v[126:129]
	v_mfma_f32_16x16x32_bf16 v[106:109], v[86:89], v[182:185], v[106:109]
	v_mfma_f32_16x16x32_bf16 v[98:101], v[110:113], v[182:185], v[98:101]
	v_mfma_f32_16x16x32_bf16 v[82:85], v[86:89], v[202:205], v[82:85]
	v_mfma_f32_16x16x32_bf16 v[74:77], v[110:113], v[202:205], v[74:77]
	v_mfma_f32_16x16x32_bf16 v[142:145], v[122:125], v[162:165], 0
	v_mfma_f32_16x16x32_bf16 v[138:141], v[146:149], v[162:165], 0
	v_mfma_f32_16x16x32_bf16 v[118:121], v[122:125], v[170:173], 0
	v_mfma_f32_16x16x32_bf16 v[114:117], v[146:149], v[170:173], 0
	v_mfma_f32_16x16x32_bf16 v[94:97], v[122:125], v[178:181], 0
	v_mfma_f32_16x16x32_bf16 v[90:93], v[146:149], v[178:181], 0
	v_mfma_f32_16x16x32_bf16 v[70:73], v[122:125], v[186:189], 0
	v_mfma_f32_16x16x32_bf16 v[66:69], v[146:149], v[186:189], 0
	v_mfma_f32_16x16x32_bf16 v[142:145], v[134:137], v[166:169], v[142:145]
	v_mfma_f32_16x16x32_bf16 v[138:141], v[150:153], v[166:169], v[138:141]
	v_mfma_f32_16x16x32_bf16 v[118:121], v[134:137], v[174:177], v[118:121]
	v_mfma_f32_16x16x32_bf16 v[114:117], v[150:153], v[174:177], v[114:117]
	v_mfma_f32_16x16x32_bf16 v[94:97], v[134:137], v[182:185], v[94:97]
	v_mfma_f32_16x16x32_bf16 v[90:93], v[150:153], v[182:185], v[90:93]
	v_mfma_f32_16x16x32_bf16 v[70:73], v[134:137], v[202:205], v[70:73]
	v_mfma_f32_16x16x32_bf16 v[66:69], v[150:153], v[202:205], v[66:69]
	s_barrier
	s_add_i32 s8, s84, s22
	v_lshl_add_u64 v[206:207], s[6:7], 0, v[194:195]
	s_mov_b32 m0, s8
	ds_read_b128 v[162:165], v212 offset:16384
	ds_read_b128 v[166:169], v212 offset:17408
	ds_read_b128 v[170:173], v212 offset:18432
	ds_read_b128 v[174:177], v212 offset:19456
	ds_read_b128 v[178:181], v212 offset:20480
	ds_read_b128 v[182:185], v212 offset:21504
	ds_read_b128 v[186:189], v212 offset:22528
	ds_read_b128 v[202:205], v212 offset:23552
	global_load_lds_dwordx4 v[206:207], off
	s_add_i32 m0, s8, 0x2000
	s_add_u32 s8, s6, 0x160000
	v_lshl_add_u64 v[208:209], s[6:7], 0, v[190:191]
	s_addc_u32 s9, s7, 0
	s_add_i32 s84, s85, s22
	global_load_lds_dwordx4 v[208:209], off
	v_lshl_add_u64 v[214:215], s[8:9], 0, v[194:195]
	s_mov_b32 m0, s84
	v_lshl_add_u64 v[216:217], s[30:31], 0, v[192:193]
	global_load_lds_dwordx4 v[214:215], off
	v_lshl_add_u64 v[214:215], s[8:9], 0, v[190:191]
	s_add_i32 m0, s84, 0x2000
	s_nop 0
	global_load_lds_dwordx4 v[214:215], off
	v_lshl_add_u64 v[214:215], s[30:31], 0, v[196:197]
	s_mov_b32 m0, s35
	s_nop 0
	global_load_lds_dwordx4 v[214:215], off
	s_mov_b32 m0, s36
	s_nop 0
	global_load_lds_dwordx4 v[216:217], off
	s_waitcnt vmcnt(24)
	s_waitcnt lgkmcnt(0)
	s_barrier
; #define PG8_STAGE(bufoff, gbase, voff) do { _Pragma("unroll") for (int _i = 0; _i < 2; ++_i) \
;         __builtin_amdgcn_global_load_lds((const unsigned*)((const char*)(gbase) + (voff)[_i]), (PG8_LAS unsigned*)(lds + (bufoff) + ldsw + _i * 8192), 16, 0, 0); } while (0)
; #define PG8_LDA(dst, b, h) do { _Pragma("unroll") for (int m = 0; m < 4; ++m) _Pragma("unroll") for (int k = 0; k < 2; ++k) dst[m][k] = *(const PG8_LAS bf16x8*)(lds + PG8_SA(b, h) + aoff + m * 2048 + k * 1024); } while (0)
; #define PG8_LDB(dst, b, h) do { _Pragma("unroll") for (int n = 0; n < 2; ++n) _Pragma("unroll") for (int k = 0; k < 2; ++k) dst[n][k] = *(const PG8_LAS bf16x8*)(lds + PG8_SB(b, h) + boff + n * 2048 + k * 1024); } while (0)
; #define PG8_MMA(ai, bj, At, Bt) do { __builtin_amdgcn_s_setprio(1); _Pragma("unroll") for (int m = 0; m < 4; ++m) _Pragma("unroll") for (int n = 0; n < 2; ++n) _Pragma("unroll") for (int k = 0; k < 2; ++k) \
;         acc[ai][bj][m][n] = __builtin_amdgcn_mfma_f32_16x16x32_bf16(Bt[n][k], At[m][k], acc[ai][bj][m][n], 0, 0, 0); __builtin_amdgcn_s_setprio(0); } while (0)
; #define PG8_WAIT_V(n) asm volatile("s_waitcnt vmcnt(" #n ")" ::: "memory")
; #define PG8_WAIT_L(n) asm volatile("s_waitcnt lgkmcnt(" #n ")" ::: "memory")
; #define PG8_BAR __builtin_amdgcn_s_barrier()
; #define PG8_SCHED __builtin_amdgcn_sched_barrier(0)
; template <class Epi, class Sched, bool ALIGN_EPI = false, bool SP2 = false>
; __device__ __forceinline__ void gemm_phase(PG8_LAS unsigned char* lds, const Gemm g, const Sched& S, const Epi& E, int wave_s) {
;     ...
;             PG8_WAIT_V(8); PG8_WAIT_L(0); PG8_BAR; PG8_MMA(1, 0, At, B0); PG8_MMA(1, 1, At, B1); PG8_BAR; PG8_SCHED;
;             PG8_LDB(B0, 1, 0); PG8_LDB(B1, 1, 1); PG8_SCHED; PG8_LDA(At, 1, 0); PG8_STAGE(PG8_SA(0, 1), a2 + hstepA, voffA);
;             PG8_WAIT_V(8); PG8_WAIT_L(0); PG8_BAR; PG8_MMA(0, 0, At, B0); PG8_MMA(0, 1, At, B1); PG8_BAR; PG8_SCHED;
;             PG8_LDA(At, 1, 1); PG8_STAGE(PG8_SB(1, 0), b3, voffB); PG8_STAGE(PG8_SB(1, 1), b3 + hstepB, voffB); PG8_STAGE(PG8_SA(1, 0), a3, voffA);
	s_waitcnt lgkmcnt(0)
	v_mfma_f32_16x16x32_bf16 v[62:65], v[78:81], v[162:165], 0
	v_mfma_f32_16x16x32_bf16 v[58:61], v[102:105], v[162:165], 0
	v_mfma_f32_16x16x32_bf16 v[46:49], v[78:81], v[170:173], 0
	v_mfma_f32_16x16x32_bf16 v[42:45], v[102:105], v[170:173], 0
	v_mfma_f32_16x16x32_bf16 v[30:33], v[78:81], v[178:181], 0
	v_mfma_f32_16x16x32_bf16 v[26:29], v[102:105], v[178:181], 0
	v_mfma_f32_16x16x32_bf16 v[14:17], v[78:81], v[186:189], 0
	v_mfma_f32_16x16x32_bf16 v[10:13], v[102:105], v[186:189], 0
	v_mfma_f32_16x16x32_bf16 v[62:65], v[86:89], v[166:169], v[62:65]
	v_mfma_f32_16x16x32_bf16 v[58:61], v[110:113], v[166:169], v[58:61]
	v_mfma_f32_16x16x32_bf16 v[46:49], v[86:89], v[174:177], v[46:49]
	v_mfma_f32_16x16x32_bf16 v[42:45], v[110:113], v[174:177], v[42:45]
	v_mfma_f32_16x16x32_bf16 v[30:33], v[86:89], v[182:185], v[30:33]
	v_mfma_f32_16x16x32_bf16 v[26:29], v[110:113], v[182:185], v[26:29]
	v_mfma_f32_16x16x32_bf16 v[14:17], v[86:89], v[202:205], v[14:17]
	v_mfma_f32_16x16x32_bf16 v[10:13], v[110:113], v[202:205], v[10:13]
	v_mfma_f32_16x16x32_bf16 v[54:57], v[122:125], v[162:165], 0
	v_mfma_f32_16x16x32_bf16 v[50:53], v[146:149], v[162:165], 0
	v_mfma_f32_16x16x32_bf16 v[38:41], v[122:125], v[170:173], 0
	v_mfma_f32_16x16x32_bf16 v[34:37], v[146:149], v[170:173], 0
	v_mfma_f32_16x16x32_bf16 v[22:25], v[122:125], v[178:181], 0
	v_mfma_f32_16x16x32_bf16 v[18:21], v[146:149], v[178:181], 0
	v_mfma_f32_16x16x32_bf16 v[6:9], v[122:125], v[186:189], 0
	v_mfma_f32_16x16x32_bf16 v[2:5], v[146:149], v[186:189], 0
	v_mfma_f32_16x16x32_bf16 v[54:57], v[134:137], v[166:169], v[54:57]
	v_mfma_f32_16x16x32_bf16 v[50:53], v[150:153], v[166:169], v[50:53]
	v_mfma_f32_16x16x32_bf16 v[38:41], v[134:137], v[174:177], v[38:41]
	v_mfma_f32_16x16x32_bf16 v[34:37], v[150:153], v[174:177], v[34:37]
	v_mfma_f32_16x16x32_bf16 v[22:25], v[134:137], v[182:185], v[22:25]
	v_mfma_f32_16x16x32_bf16 v[18:21], v[150:153], v[182:185], v[18:21]
	v_mfma_f32_16x16x32_bf16 v[6:9], v[134:137], v[202:205], v[6:9]
	v_mfma_f32_16x16x32_bf16 v[2:5], v[150:153], v[202:205], v[2:5]
	s_barrier
	s_add_i32 s84, 0, 0x18000
	s_add_i32 s85, 0, 0x1c000
	v_add_u32_e32 v110, s84, v211
	v_add_u32_e32 v150, s85, v211
	ds_read_b128 v[78:81], v110
	ds_read_b128 v[86:89], v110 offset:1024
	ds_read_b128 v[102:105], v110 offset:2048
	ds_read_b128 v[110:113], v110 offset:3072
	ds_read_b128 v[122:125], v150
	ds_read_b128 v[134:137], v150 offset:1024
	ds_read_b128 v[146:149], v150 offset:2048
	ds_read_b128 v[150:153], v150 offset:3072
	s_add_u32 s8, s30, 0x160000
	s_addc_u32 s9, s31, 0
	s_mov_b32 m0, s37
	v_lshl_add_u64 v[218:219], s[8:9], 0, v[196:197]
	ds_read_b128 v[162:165], v212 offset:32768
	ds_read_b128 v[166:169], v212 offset:33792
	ds_read_b128 v[170:173], v212 offset:34816
	ds_read_b128 v[174:177], v212 offset:35840
	ds_read_b128 v[178:181], v212 offset:36864
	ds_read_b128 v[182:185], v212 offset:37888
	ds_read_b128 v[186:189], v212 offset:38912
	ds_read_b128 v[202:205], v212 offset:39936
	global_load_lds_dwordx4 v[218:219], off
	v_lshl_add_u64 v[218:219], s[8:9], 0, v[192:193]
	s_mov_b32 m0, s40
	s_nop 0
	global_load_lds_dwordx4 v[218:219], off
	s_waitcnt vmcnt(24)
	s_waitcnt lgkmcnt(0)
	s_barrier
	s_waitcnt lgkmcnt(0)
	v_mfma_f32_16x16x32_bf16 v[158:161], v[78:81], v[162:165], v[158:161]
	v_mfma_f32_16x16x32_bf16 v[154:157], v[102:105], v[162:165], v[154:157]
	v_mfma_f32_16x16x32_bf16 v[130:133], v[78:81], v[170:173], v[130:133]
	v_mfma_f32_16x16x32_bf16 v[126:129], v[102:105], v[170:173], v[126:129]
	v_mfma_f32_16x16x32_bf16 v[106:109], v[78:81], v[178:181], v[106:109]
	v_mfma_f32_16x16x32_bf16 v[98:101], v[102:105], v[178:181], v[98:101]
	v_mfma_f32_16x16x32_bf16 v[82:85], v[78:81], v[186:189], v[82:85]
	v_mfma_f32_16x16x32_bf16 v[74:77], v[102:105], v[186:189], v[74:77]
	v_mfma_f32_16x16x32_bf16 v[158:161], v[86:89], v[166:169], v[158:161]
	v_mfma_f32_16x16x32_bf16 v[154:157], v[110:113], v[166:169], v[154:157]
	v_mfma_f32_16x16x32_bf16 v[130:133], v[86:89], v[174:177], v[130:133]
	v_mfma_f32_16x16x32_bf16 v[126:129], v[110:113], v[174:177], v[126:129]
	v_mfma_f32_16x16x32_bf16 v[106:109], v[86:89], v[182:185], v[106:109]
	v_mfma_f32_16x16x32_bf16 v[98:101], v[110:113], v[182:185], v[98:101]
	v_mfma_f32_16x16x32_bf16 v[82:85], v[86:89], v[202:205], v[82:85]
	v_mfma_f32_16x16x32_bf16 v[74:77], v[110:113], v[202:205], v[74:77]
	v_mfma_f32_16x16x32_bf16 v[142:145], v[122:125], v[162:165], v[142:145]
	v_mfma_f32_16x16x32_bf16 v[138:141], v[146:149], v[162:165], v[138:141]
	v_mfma_f32_16x16x32_bf16 v[118:121], v[122:125], v[170:173], v[118:121]
	v_mfma_f32_16x16x32_bf16 v[114:117], v[146:149], v[170:173], v[114:117]
	v_mfma_f32_16x16x32_bf16 v[94:97], v[122:125], v[178:181], v[94:97]
	v_mfma_f32_16x16x32_bf16 v[90:93], v[146:149], v[178:181], v[90:93]
	v_mfma_f32_16x16x32_bf16 v[70:73], v[122:125], v[186:189], v[70:73]
	v_mfma_f32_16x16x32_bf16 v[66:69], v[146:149], v[186:189], v[66:69]
	v_mfma_f32_16x16x32_bf16 v[142:145], v[134:137], v[166:169], v[142:145]
	v_mfma_f32_16x16x32_bf16 v[138:141], v[150:153], v[166:169], v[138:141]
	v_mfma_f32_16x16x32_bf16 v[118:121], v[134:137], v[174:177], v[118:121]
	v_mfma_f32_16x16x32_bf16 v[114:117], v[150:153], v[174:177], v[114:117]
	v_mfma_f32_16x16x32_bf16 v[94:97], v[134:137], v[182:185], v[94:97]
	v_mfma_f32_16x16x32_bf16 v[90:93], v[150:153], v[182:185], v[90:93]
	v_mfma_f32_16x16x32_bf16 v[70:73], v[134:137], v[202:205], v[70:73]
	v_mfma_f32_16x16x32_bf16 v[66:69], v[150:153], v[202:205], v[66:69]
	s_barrier
; #define PG8_STAGE(bufoff, gbase, voff) do { _Pragma("unroll") for (int _i = 0; _i < 2; ++_i) \
;         __builtin_amdgcn_global_load_lds((const unsigned*)((const char*)(gbase) + (voff)[_i]), (PG8_LAS unsigned*)(lds + (bufoff) + ldsw + _i * 8192), 16, 0, 0); } while (0)
; #define PG8_LDA(dst, b, h) do { _Pragma("unroll") for (int m = 0; m < 4; ++m) _Pragma("unroll") for (int k = 0; k < 2; ++k) dst[m][k] = *(const PG8_LAS bf16x8*)(lds + PG8_SA(b, h) + aoff + m * 2048 + k * 1024); } while (0)
; #define PG8_MMA(ai, bj, At, Bt) do { __builtin_amdgcn_s_setprio(1); _Pragma("unroll") for (int m = 0; m < 4; ++m) _Pragma("unroll") for (int n = 0; n < 2; ++n) _Pragma("unroll") for (int k = 0; k < 2; ++k) \
;         acc[ai][bj][m][n] = __builtin_amdgcn_mfma_f32_16x16x32_bf16(Bt[n][k], At[m][k], acc[ai][bj][m][n], 0, 0, 0); __builtin_amdgcn_s_setprio(0); } while (0)
; #define PG8_WAIT_V(n) asm volatile("s_waitcnt vmcnt(" #n ")" ::: "memory")
; #define PG8_WAIT_L(n) asm volatile("s_waitcnt lgkmcnt(" #n ")" ::: "memory")
; #define PG8_BAR __builtin_amdgcn_s_barrier()
; #define PG8_SCHED __builtin_amdgcn_sched_barrier(0)
; template <class Epi, class Sched, bool ALIGN_EPI = false, bool SP2 = false>
; __device__ __forceinline__ void gemm_phase(PG8_LAS unsigned char* lds, const Gemm g, const Sched& S, const Epi& E, int wave_s) {
;     ...
;             PG8_LDA(At, 1, 1); PG8_STAGE(PG8_SB(1, 0), b3, voffB); PG8_STAGE(PG8_SB(1, 1), b3 + hstepB, voffB); PG8_STAGE(PG8_SA(1, 0), a3, voffA);
;             PG8_WAIT_V(8); PG8_WAIT_L(0); PG8_BAR; PG8_MMA(1, 0, At, B0); PG8_MMA(1, 1, At, B1); PG8_BAR; PG8_SCHED;
	s_add_i32 s8, s84, s22
	v_lshl_add_u64 v[206:207], v[206:207], 0, s[60:61]
	s_mov_b32 m0, s8
	ds_read_b128 v[162:165], v212 offset:49152
	ds_read_b128 v[166:169], v212 offset:50176
	ds_read_b128 v[170:173], v212 offset:51200
	ds_read_b128 v[174:177], v212 offset:52224
	ds_read_b128 v[178:181], v212 offset:53248
	ds_read_b128 v[182:185], v212 offset:54272
	ds_read_b128 v[186:189], v212 offset:55296
	ds_read_b128 v[202:205], v212 offset:56320
	global_load_lds_dwordx4 v[206:207], off
	s_add_i32 m0, s8, 0x2000
	s_add_u32 s6, s6, 0x160080
	v_lshl_add_u64 v[206:207], v[208:209], 0, s[60:61]
	s_addc_u32 s7, s7, 0
	s_add_i32 s8, s85, s22
	global_load_lds_dwordx4 v[206:207], off
	v_lshl_add_u64 v[206:207], s[6:7], 0, v[194:195]
	s_mov_b32 m0, s8
	s_nop 0
	global_load_lds_dwordx4 v[206:207], off
	v_lshl_add_u64 v[206:207], s[6:7], 0, v[190:191]
	s_add_i32 m0, s8, 0x2000
	s_nop 0
	global_load_lds_dwordx4 v[206:207], off
	v_lshl_add_u64 v[206:207], v[214:215], 0, s[60:61]
	s_mov_b32 m0, s44
	s_nop 0
	global_load_lds_dwordx4 v[206:207], off
	v_lshl_add_u64 v[206:207], v[216:217], 0, s[60:61]
	s_mov_b32 m0, s45
	s_nop 0
	global_load_lds_dwordx4 v[206:207], off
	s_waitcnt vmcnt(8)
	s_waitcnt lgkmcnt(0)
	s_barrier
	s_waitcnt lgkmcnt(0)
	v_mfma_f32_16x16x32_bf16 v[62:65], v[78:81], v[162:165], v[62:65]
	v_mfma_f32_16x16x32_bf16 v[58:61], v[102:105], v[162:165], v[58:61]
	v_mfma_f32_16x16x32_bf16 v[46:49], v[78:81], v[170:173], v[46:49]
	v_mfma_f32_16x16x32_bf16 v[42:45], v[102:105], v[170:173], v[42:45]
	v_mfma_f32_16x16x32_bf16 v[30:33], v[78:81], v[178:181], v[30:33]
	v_mfma_f32_16x16x32_bf16 v[26:29], v[102:105], v[178:181], v[26:29]
	v_mfma_f32_16x16x32_bf16 v[14:17], v[78:81], v[186:189], v[14:17]
	v_mfma_f32_16x16x32_bf16 v[10:13], v[102:105], v[186:189], v[10:13]
	v_mfma_f32_16x16x32_bf16 v[62:65], v[86:89], v[166:169], v[62:65]
	v_mfma_f32_16x16x32_bf16 v[58:61], v[110:113], v[166:169], v[58:61]
	v_mfma_f32_16x16x32_bf16 v[46:49], v[86:89], v[174:177], v[46:49]
	v_mfma_f32_16x16x32_bf16 v[42:45], v[110:113], v[174:177], v[42:45]
	v_mfma_f32_16x16x32_bf16 v[30:33], v[86:89], v[182:185], v[30:33]
	v_mfma_f32_16x16x32_bf16 v[26:29], v[110:113], v[182:185], v[26:29]
	v_mfma_f32_16x16x32_bf16 v[14:17], v[86:89], v[202:205], v[14:17]
	v_mfma_f32_16x16x32_bf16 v[10:13], v[110:113], v[202:205], v[10:13]
	v_mfma_f32_16x16x32_bf16 v[54:57], v[122:125], v[162:165], v[54:57]
	v_mfma_f32_16x16x32_bf16 v[50:53], v[146:149], v[162:165], v[50:53]
	v_mfma_f32_16x16x32_bf16 v[38:41], v[122:125], v[170:173], v[38:41]
	v_mfma_f32_16x16x32_bf16 v[34:37], v[146:149], v[170:173], v[34:37]
	v_mfma_f32_16x16x32_bf16 v[22:25], v[122:125], v[178:181], v[22:25]
	v_mfma_f32_16x16x32_bf16 v[18:21], v[146:149], v[178:181], v[18:21]
	v_mfma_f32_16x16x32_bf16 v[6:9], v[122:125], v[186:189], v[6:9]
	v_mfma_f32_16x16x32_bf16 v[2:5], v[146:149], v[186:189], v[2:5]
	v_mfma_f32_16x16x32_bf16 v[54:57], v[134:137], v[166:169], v[54:57]
	v_mfma_f32_16x16x32_bf16 v[50:53], v[150:153], v[166:169], v[50:53]
	v_mfma_f32_16x16x32_bf16 v[38:41], v[134:137], v[174:177], v[38:41]
	v_mfma_f32_16x16x32_bf16 v[34:37], v[150:153], v[174:177], v[34:37]
	v_mfma_f32_16x16x32_bf16 v[22:25], v[134:137], v[182:185], v[22:25]
	v_mfma_f32_16x16x32_bf16 v[18:21], v[150:153], v[182:185], v[18:21]
	v_mfma_f32_16x16x32_bf16 v[6:9], v[134:137], v[202:205], v[6:9]
	v_mfma_f32_16x16x32_bf16 v[2:5], v[150:153], v[202:205], v[2:5]
	s_barrier
	s_add_i32 s81, s81, 2
	s_add_u32 s2, s2, 0x100
	s_addc_u32 s3, s3, 0
	s_cmpk_gt_u32 s81, 0x55
	s_mov_b64 s[8:9], s[4:5]
